# lru input stage: remainder batch's wait and LDS writes deferred behind the main batches (single round trip for the stage)
# baseline (speedup 1.0000x reference)
; __device__ __forceinline__ float bf2f(bf16_t v) { return __uint_as_float(((unsigned)v) << 16); }
; __device__ void lru_local_unit(const Params& p, unsigned char* smem, int unit) {
;   const int tid = threadIdx.x & 255, lane = tid & 63, wid = tid >> 6, l15 = lane & 15, q4 = lane >> 4;
;   const int hh = unit & 15, c = (unit >> 4) & 15, b = unit >> 8;
;   const int t0 = b * 2048 + c * 128, ch0 = hh * 64;
;   unsigned char* ws = p.ws;
;   const bf16_t* proj = (const bf16_t*)(ws + OFF_PROJ);
;   float* R1 = (float*)smem;
;   float* R2 = (float*)(smem + 33536);
;   float* R3 = (float*)(smem + 33536 + 32768);
; #pragma unroll 11
;   for (int e = tid; e < 131 * 64; e += HTHR) {
;     const int r = e >> 6, j = e & 63, tt = r - 3;
;     float v = 0.f;
;     if (c * 128 + tt >= 0) v = bf2f(proj[(size_t)(t0 + tt) * LDP + ch0 + j]);
.LBB0_499:
	v_add_u32_e32 v2, s84, v165
	v_and_b32_e32 v16, 15, v2
	v_lshlrev_b32_e32 v127, 3, v2
	s_movk_i32 s3, 0xf87f
	v_lshlrev_b32_e32 v68, 7, v16
	v_and_b32_e32 v29, 0xffffff80, v116
	v_bitop3_b32 v4, v127, s3, v127 bitop3:0xcf
	v_lshl_add_u64 v[2:3], v[70:71], 0, v[68:69]
	v_mov_b32_e32 v27, v104
	v_mov_b32_e32 v26, v112
	v_mov_b32_e32 v5, v117
	s_waitcnt lgkmcnt(0)
	s_and_saveexec_b64 s[66:67], s[4:5]
	s_cbranch_execz .LBB0_505
	v_mov_b32_e32 v5, v114
	v_mov_b32_e32 v6, v117
	v_mov_b32_e32 v7, v115
	v_mov_b32_e32 v27, v104
	v_add_u32_e32 v32, 0, v6
	v_cmp_lt_u32_e32 vcc, 0, v5
	v_cmp_gt_i32_e64 s[80:81], v32, v4
	v_mov_b32_e32 v140, 0
	s_nop 1
	s_and_b64 vcc, vcc, s[80:81]
	s_and_saveexec_b64 s[80:81], vcc
	v_add_u32_e32 v32, v29, v32
	v_mad_i64_i32 v[32:33], s[12:13], v32, s89, v[2:3]
	global_load_ushort v140, v[32:33], off
	s_or_b64 exec, exec, s[80:81]
	v_add_u32_e32 v32, 4, v6
	v_cmp_lt_u32_e32 vcc, 1, v5
	v_cmp_gt_i32_e64 s[80:81], v32, v4
	v_mov_b32_e32 v141, 0
	s_nop 1
	s_and_b64 vcc, vcc, s[80:81]
	s_and_saveexec_b64 s[80:81], vcc
	v_add_u32_e32 v32, v29, v32
	v_mad_i64_i32 v[32:33], s[12:13], v32, s89, v[2:3]
	global_load_ushort v141, v[32:33], off
	s_or_b64 exec, exec, s[80:81]
	v_add_u32_e32 v32, 8, v6
	v_cmp_lt_u32_e32 vcc, 2, v5
	v_cmp_gt_i32_e64 s[80:81], v32, v4
	v_mov_b32_e32 v142, 0
	s_nop 1
	s_and_b64 vcc, vcc, s[80:81]
	s_and_saveexec_b64 s[80:81], vcc
	v_add_u32_e32 v32, v29, v32
	v_mad_i64_i32 v[32:33], s[12:13], v32, s89, v[2:3]
	global_load_ushort v142, v[32:33], off
	s_or_b64 exec, exec, s[80:81]
	v_add_u32_e32 v32, 12, v6
	v_cmp_lt_u32_e32 vcc, 3, v5
	v_cmp_gt_i32_e64 s[80:81], v32, v4
	v_mov_b32_e32 v143, 0
	s_nop 1
	s_and_b64 vcc, vcc, s[80:81]
	s_and_saveexec_b64 s[80:81], vcc
	v_add_u32_e32 v32, v29, v32
	v_mad_i64_i32 v[32:33], s[12:13], v32, s89, v[2:3]
	global_load_ushort v143, v[32:33], off
	s_or_b64 exec, exec, s[80:81]
	v_add_u32_e32 v32, 16, v6
	v_cmp_lt_u32_e32 vcc, 4, v5
	v_cmp_gt_i32_e64 s[80:81], v32, v4
	v_mov_b32_e32 v144, 0
	s_nop 1
	s_and_b64 vcc, vcc, s[80:81]
	s_and_saveexec_b64 s[80:81], vcc
	v_add_u32_e32 v32, v29, v32
	v_mad_i64_i32 v[32:33], s[12:13], v32, s89, v[2:3]
	global_load_ushort v144, v[32:33], off
	s_or_b64 exec, exec, s[80:81]
	v_add_u32_e32 v32, 20, v6
	v_cmp_lt_u32_e32 vcc, 5, v5
	v_cmp_gt_i32_e64 s[80:81], v32, v4
	v_mov_b32_e32 v145, 0
	s_nop 1
	s_and_b64 vcc, vcc, s[80:81]
	s_and_saveexec_b64 s[80:81], vcc
	v_add_u32_e32 v32, v29, v32
	v_mad_i64_i32 v[32:33], s[12:13], v32, s89, v[2:3]
	global_load_ushort v145, v[32:33], off
	s_or_b64 exec, exec, s[80:81]
	v_add_u32_e32 v32, 24, v6
	v_cmp_lt_u32_e32 vcc, 6, v5
	v_cmp_gt_i32_e64 s[80:81], v32, v4
	v_mov_b32_e32 v146, 0
	s_nop 1
	s_and_b64 vcc, vcc, s[80:81]
	s_and_saveexec_b64 s[80:81], vcc
	v_add_u32_e32 v32, v29, v32
	v_mad_i64_i32 v[32:33], s[12:13], v32, s89, v[2:3]
	global_load_ushort v146, v[32:33], off
	s_or_b64 exec, exec, s[80:81]
	v_add_u32_e32 v32, 28, v6
	v_cmp_lt_u32_e32 vcc, 7, v5
	v_cmp_gt_i32_e64 s[80:81], v32, v4
	v_mov_b32_e32 v147, 0
	s_nop 1
	s_and_b64 vcc, vcc, s[80:81]
	s_and_saveexec_b64 s[80:81], vcc
	v_add_u32_e32 v32, v29, v32
	v_mad_i64_i32 v[32:33], s[12:13], v32, s89, v[2:3]
	global_load_ushort v147, v[32:33], off
	s_or_b64 exec, exec, s[80:81]
	v_add_u32_e32 v32, 32, v6
	v_cmp_lt_u32_e32 vcc, 8, v5
	v_cmp_gt_i32_e64 s[80:81], v32, v4
	v_mov_b32_e32 v148, 0
	s_nop 1
	s_and_b64 vcc, vcc, s[80:81]
	s_and_saveexec_b64 s[80:81], vcc
	v_add_u32_e32 v32, v29, v32
	v_mad_i64_i32 v[32:33], s[12:13], v32, s89, v[2:3]
	global_load_ushort v148, v[32:33], off
	s_or_b64 exec, exec, s[80:81]
	v_add_u32_e32 v32, 36, v6
	v_cmp_lt_u32_e32 vcc, 9, v5
	v_cmp_gt_i32_e64 s[80:81], v32, v4
	v_mov_b32_e32 v149, 0
	s_nop 1
	s_and_b64 vcc, vcc, s[80:81]
	s_and_saveexec_b64 s[80:81], vcc
	v_add_u32_e32 v32, v29, v32
	v_mad_i64_i32 v[32:33], s[12:13], v32, s89, v[2:3]
	global_load_ushort v149, v[32:33], off
	s_or_b64 exec, exec, s[80:81]
	v_mov_b32_e32 v226, v7
	v_mov_b32_e32 v227, v5
	v_lshl_add_u32 v27, v5, 8, v27
	v_lshrrev_b32_e32 v5, 6, v27
	v_lshlrev_b32_e32 v26, 2, v27
	v_add_u32_e32 v5, -3, v5

; __device__ __forceinline__ float bf2f(bf16_t v) { return __uint_as_float(((unsigned)v) << 16); }
; __device__ void lru_local_unit(const Params& p, unsigned char* smem, int unit) {
;     ...
; #pragma unroll 11
;   for (int e = tid; e < 131 * 64; e += HTHR) {
;     const int r = e >> 6, j = e & 63, tt = r - 3;
;     float v = 0.f;
;     if (c * 128 + tt >= 0) v = bf2f(proj[(size_t)(t0 + tt) * LDP + ch0 + j]);
;     R1[e] = v;
;   }
.LBB0_507:
	s_mov_b64 s[66:67], exec
	s_movk_i32 s12, 0x15bf
	s_mov_b32 s3, 0
	v_add_u32_e32 v32, s3, v5
	v_cmp_gt_i32_e32 vcc, v32, v4
	v_mov_b32_e32 v215, 0
	s_and_saveexec_b64 s[78:79], vcc
	v_add_u32_e32 v32, s3, v29
	v_mad_i64_i32 v[32:33], s[12:13], v32, s89, v[2:3]
	global_load_ushort v215, v[32:33], off
	s_or_b64 exec, exec, s[78:79]
	v_add_u32_e32 v32, s3, v27
	v_cmp_gt_i32_e32 vcc, v32, v4
	v_mov_b32_e32 v216, 0
	s_and_saveexec_b64 s[78:79], vcc
	v_add_u32_e32 v32, s3, v28
	v_mad_i64_i32 v[32:33], s[12:13], v32, s89, v[2:3]
	global_load_ushort v216, v[32:33], off
	s_or_b64 exec, exec, s[78:79]
	v_add_u32_e32 v32, s3, v24
	v_cmp_gt_i32_e32 vcc, v32, v4
	v_mov_b32_e32 v217, 0
	s_and_saveexec_b64 s[78:79], vcc
	v_add_u32_e32 v32, s3, v25
	v_mad_i64_i32 v[32:33], s[12:13], v32, s89, v[2:3]
	global_load_ushort v217, v[32:33], off
	s_or_b64 exec, exec, s[78:79]
	v_add_u32_e32 v32, s3, v22
	v_cmp_gt_i32_e32 vcc, v32, v4
	v_mov_b32_e32 v218, 0
	s_and_saveexec_b64 s[78:79], vcc
	v_add_u32_e32 v32, s3, v23
	v_mad_i64_i32 v[32:33], s[12:13], v32, s89, v[2:3]
	global_load_ushort v218, v[32:33], off
	s_or_b64 exec, exec, s[78:79]
	v_add_u32_e32 v32, s3, v20
	v_cmp_gt_i32_e32 vcc, v32, v4
	v_mov_b32_e32 v219, 0
	s_and_saveexec_b64 s[78:79], vcc
	v_add_u32_e32 v32, s3, v21
	v_mad_i64_i32 v[32:33], s[12:13], v32, s89, v[2:3]
	global_load_ushort v219, v[32:33], off
	s_or_b64 exec, exec, s[78:79]
	v_add_u32_e32 v32, s3, v18
	v_cmp_gt_i32_e32 vcc, v32, v4
	v_mov_b32_e32 v220, 0
	s_and_saveexec_b64 s[78:79], vcc
	v_add_u32_e32 v32, s3, v19
	v_mad_i64_i32 v[32:33], s[12:13], v32, s89, v[2:3]
	global_load_ushort v220, v[32:33], off
	s_or_b64 exec, exec, s[78:79]
	v_add_u32_e32 v32, s3, v15
	v_cmp_gt_i32_e32 vcc, v32, v4
	v_mov_b32_e32 v221, 0
	s_and_saveexec_b64 s[78:79], vcc
	v_add_u32_e32 v32, s3, v17
	v_mad_i64_i32 v[32:33], s[12:13], v32, s89, v[2:3]
	global_load_ushort v221, v[32:33], off
	s_or_b64 exec, exec, s[78:79]
	v_add_u32_e32 v32, s3, v13
	v_cmp_gt_i32_e32 vcc, v32, v4
	v_mov_b32_e32 v222, 0
	s_and_saveexec_b64 s[78:79], vcc
	v_add_u32_e32 v32, s3, v14
	v_mad_i64_i32 v[32:33], s[12:13], v32, s89, v[2:3]
	global_load_ushort v222, v[32:33], off
	s_or_b64 exec, exec, s[78:79]
	v_add_u32_e32 v32, s3, v11
	v_cmp_gt_i32_e32 vcc, v32, v4
	v_mov_b32_e32 v223, 0
	s_and_saveexec_b64 s[78:79], vcc
	v_add_u32_e32 v32, s3, v12
	v_mad_i64_i32 v[32:33], s[12:13], v32, s89, v[2:3]
	global_load_ushort v223, v[32:33], off
	s_or_b64 exec, exec, s[78:79]
	v_add_u32_e32 v32, s3, v9
	v_cmp_gt_i32_e32 vcc, v32, v4
	v_mov_b32_e32 v224, 0
	s_and_saveexec_b64 s[78:79], vcc
	v_add_u32_e32 v32, s3, v10
	v_mad_i64_i32 v[32:33], s[12:13], v32, s89, v[2:3]
	global_load_ushort v224, v[32:33], off
	s_or_b64 exec, exec, s[78:79]
	v_add_u32_e32 v32, s3, v7
	v_cmp_gt_i32_e32 vcc, v32, v4
	v_mov_b32_e32 v225, 0
	s_and_saveexec_b64 s[78:79], vcc
	v_add_u32_e32 v32, s3, v8
	v_mad_i64_i32 v[32:33], s[12:13], v32, s89, v[2:3]
	global_load_ushort v225, v[32:33], off
	s_or_b64 exec, exec, s[78:79]
	v_add_u32_e32 v6, 0xb00, v6
	s_movk_i32 s12, 0x15bf
	v_cmp_ge_u32_e32 vcc, s12, v6
	s_and_b64 s[72:73], exec, vcc
	s_mov_b64 exec, s[72:73]
	s_mov_b32 s3, 44
	v_add_u32_e32 v32, s3, v5
	v_cmp_gt_i32_e32 vcc, v32, v4
	v_mov_b32_e32 v193, 0
	s_and_saveexec_b64 s[78:79], vcc
	v_add_u32_e32 v32, s3, v29
	v_mad_i64_i32 v[32:33], s[12:13], v32, s89, v[2:3]
	global_load_ushort v193, v[32:33], off
	s_or_b64 exec, exec, s[78:79]
	v_add_u32_e32 v32, s3, v27
	v_cmp_gt_i32_e32 vcc, v32, v4
	v_mov_b32_e32 v194, 0
	s_and_saveexec_b64 s[78:79], vcc
	v_add_u32_e32 v32, s3, v28
	v_mad_i64_i32 v[32:33], s[12:13], v32, s89, v[2:3]
	global_load_ushort v194, v[32:33], off
	s_or_b64 exec, exec, s[78:79]
	v_add_u32_e32 v32, s3, v24
	v_cmp_gt_i32_e32 vcc, v32, v4
	v_mov_b32_e32 v195, 0
	s_and_saveexec_b64 s[78:79], vcc
	v_add_u32_e32 v32, s3, v25
	v_mad_i64_i32 v[32:33], s[12:13], v32, s89, v[2:3]
	global_load_ushort v195, v[32:33], off
	s_or_b64 exec, exec, s[78:79]
	v_add_u32_e32 v32, s3, v22
	v_cmp_gt_i32_e32 vcc, v32, v4
	v_mov_b32_e32 v196, 0
	s_and_saveexec_b64 s[78:79], vcc
	v_add_u32_e32 v32, s3, v23
	v_mad_i64_i32 v[32:33], s[12:13], v32, s89, v[2:3]
	global_load_ushort v196, v[32:33], off
	s_or_b64 exec, exec, s[78:79]
	v_add_u32_e32 v32, s3, v20
	v_cmp_gt_i32_e32 vcc, v32, v4
	v_mov_b32_e32 v197, 0
	s_and_saveexec_b64 s[78:79], vcc
	v_add_u32_e32 v32, s3, v21
	v_mad_i64_i32 v[32:33], s[12:13], v32, s89, v[2:3]
	global_load_ushort v197, v[32:33], off
	s_or_b64 exec, exec, s[78:79]
	v_add_u32_e32 v32, s3, v18
	v_cmp_gt_i32_e32 vcc, v32, v4
	v_mov_b32_e32 v198, 0
	s_and_saveexec_b64 s[78:79], vcc
	v_add_u32_e32 v32, s3, v19
	v_mad_i64_i32 v[32:33], s[12:13], v32, s89, v[2:3]
	global_load_ushort v198, v[32:33], off
	s_or_b64 exec, exec, s[78:79]
	v_add_u32_e32 v32, s3, v15
	v_cmp_gt_i32_e32 vcc, v32, v4
	v_mov_b32_e32 v199, 0
	s_and_saveexec_b64 s[78:79], vcc
	v_add_u32_e32 v32, s3, v17
	v_mad_i64_i32 v[32:33], s[12:13], v32, s89, v[2:3]
	global_load_ushort v199, v[32:33], off
	s_or_b64 exec, exec, s[78:79]
	v_add_u32_e32 v32, s3, v13
	v_cmp_gt_i32_e32 vcc, v32, v4
	v_mov_b32_e32 v200, 0
	s_and_saveexec_b64 s[78:79], vcc
	v_add_u32_e32 v32, s3, v14
	v_mad_i64_i32 v[32:33], s[12:13], v32, s89, v[2:3]
	global_load_ushort v200, v[32:33], off
	s_or_b64 exec, exec, s[78:79]
	v_add_u32_e32 v32, s3, v11
	v_cmp_gt_i32_e32 vcc, v32, v4
	v_mov_b32_e32 v201, 0
	s_and_saveexec_b64 s[78:79], vcc
	v_add_u32_e32 v32, s3, v12
	v_mad_i64_i32 v[32:33], s[12:13], v32, s89, v[2:3]
	global_load_ushort v201, v[32:33], off
	s_or_b64 exec, exec, s[78:79]
	v_add_u32_e32 v32, s3, v9
	v_cmp_gt_i32_e32 vcc, v32, v4
; __device__ __forceinline__ float bf2f(bf16_t v) { return __uint_as_float(((unsigned)v) << 16); }
; __device__ void lru_local_unit(const Params& p, unsigned char* smem, int unit) {
;     ...
; #pragma unroll 11
;   for (int e = tid; e < 131 * 64; e += HTHR) {
;     const int r = e >> 6, j = e & 63, tt = r - 3;
;     float v = 0.f;
;     if (c * 128 + tt >= 0) v = bf2f(proj[(size_t)(t0 + tt) * LDP + ch0 + j]);
;     R1[e] = v;
;   }
	v_mov_b32_e32 v202, 0
	s_and_saveexec_b64 s[78:79], vcc
	v_add_u32_e32 v32, s3, v10
	v_mad_i64_i32 v[32:33], s[12:13], v32, s89, v[2:3]
	global_load_ushort v202, v[32:33], off
	s_or_b64 exec, exec, s[78:79]
	v_add_u32_e32 v32, s3, v7
	v_cmp_gt_i32_e32 vcc, v32, v4
	v_mov_b32_e32 v203, 0
	s_and_saveexec_b64 s[78:79], vcc
	v_add_u32_e32 v32, s3, v8
	v_mad_i64_i32 v[32:33], s[12:13], v32, s89, v[2:3]
	global_load_ushort v203, v[32:33], off
	s_or_b64 exec, exec, s[78:79]
	v_add_u32_e32 v6, 0xb00, v6
	s_movk_i32 s12, 0x15bf
	v_cmp_ge_u32_e32 vcc, s12, v6
	s_and_b64 s[74:75], exec, vcc
	s_mov_b64 exec, s[74:75]
	s_mov_b32 s3, 88
	v_add_u32_e32 v32, s3, v5
	v_cmp_gt_i32_e32 vcc, v32, v4
	v_mov_b32_e32 v204, 0
	s_and_saveexec_b64 s[78:79], vcc
	v_add_u32_e32 v32, s3, v29
	v_mad_i64_i32 v[32:33], s[12:13], v32, s89, v[2:3]
	global_load_ushort v204, v[32:33], off
	s_or_b64 exec, exec, s[78:79]
	v_add_u32_e32 v32, s3, v27
	v_cmp_gt_i32_e32 vcc, v32, v4
	v_mov_b32_e32 v205, 0
	s_and_saveexec_b64 s[78:79], vcc
	v_add_u32_e32 v32, s3, v28
	v_mad_i64_i32 v[32:33], s[12:13], v32, s89, v[2:3]
	global_load_ushort v205, v[32:33], off
	s_or_b64 exec, exec, s[78:79]
	v_add_u32_e32 v32, s3, v24
	v_cmp_gt_i32_e32 vcc, v32, v4
	v_mov_b32_e32 v206, 0
	s_and_saveexec_b64 s[78:79], vcc
	v_add_u32_e32 v32, s3, v25
	v_mad_i64_i32 v[32:33], s[12:13], v32, s89, v[2:3]
	global_load_ushort v206, v[32:33], off
	s_or_b64 exec, exec, s[78:79]
	v_add_u32_e32 v32, s3, v22
	v_cmp_gt_i32_e32 vcc, v32, v4
	v_mov_b32_e32 v207, 0
	s_and_saveexec_b64 s[78:79], vcc
	v_add_u32_e32 v32, s3, v23
	v_mad_i64_i32 v[32:33], s[12:13], v32, s89, v[2:3]
	global_load_ushort v207, v[32:33], off
	s_or_b64 exec, exec, s[78:79]
	v_add_u32_e32 v32, s3, v20
	v_cmp_gt_i32_e32 vcc, v32, v4
	v_mov_b32_e32 v208, 0
	s_and_saveexec_b64 s[78:79], vcc
	v_add_u32_e32 v32, s3, v21
	v_mad_i64_i32 v[32:33], s[12:13], v32, s89, v[2:3]
	global_load_ushort v208, v[32:33], off
	s_or_b64 exec, exec, s[78:79]
	v_add_u32_e32 v32, s3, v18
	v_cmp_gt_i32_e32 vcc, v32, v4
	v_mov_b32_e32 v209, 0
	s_and_saveexec_b64 s[78:79], vcc
	v_add_u32_e32 v32, s3, v19
	v_mad_i64_i32 v[32:33], s[12:13], v32, s89, v[2:3]
	global_load_ushort v209, v[32:33], off
	s_or_b64 exec, exec, s[78:79]
	v_add_u32_e32 v32, s3, v15
	v_cmp_gt_i32_e32 vcc, v32, v4
	v_mov_b32_e32 v210, 0
	s_and_saveexec_b64 s[78:79], vcc
	v_add_u32_e32 v32, s3, v17
	v_mad_i64_i32 v[32:33], s[12:13], v32, s89, v[2:3]
	global_load_ushort v210, v[32:33], off
	s_or_b64 exec, exec, s[78:79]
	v_add_u32_e32 v32, s3, v13
	v_cmp_gt_i32_e32 vcc, v32, v4
	v_mov_b32_e32 v211, 0
	s_and_saveexec_b64 s[78:79], vcc
	v_add_u32_e32 v32, s3, v14
	v_mad_i64_i32 v[32:33], s[12:13], v32, s89, v[2:3]
	global_load_ushort v211, v[32:33], off
	s_or_b64 exec, exec, s[78:79]
	v_add_u32_e32 v32, s3, v11
	v_cmp_gt_i32_e32 vcc, v32, v4
	v_mov_b32_e32 v212, 0
	s_and_saveexec_b64 s[78:79], vcc
	v_add_u32_e32 v32, s3, v12
	v_mad_i64_i32 v[32:33], s[12:13], v32, s89, v[2:3]
	global_load_ushort v212, v[32:33], off
	s_or_b64 exec, exec, s[78:79]
	v_add_u32_e32 v32, s3, v9
	v_cmp_gt_i32_e32 vcc, v32, v4
	v_mov_b32_e32 v213, 0
	s_and_saveexec_b64 s[78:79], vcc
	v_add_u32_e32 v32, s3, v10
	v_mad_i64_i32 v[32:33], s[12:13], v32, s89, v[2:3]
	global_load_ushort v213, v[32:33], off
	s_or_b64 exec, exec, s[78:79]
	v_add_u32_e32 v32, s3, v7
	v_cmp_gt_i32_e32 vcc, v32, v4
	v_mov_b32_e32 v214, 0
	s_and_saveexec_b64 s[78:79], vcc
	v_add_u32_e32 v32, s3, v8
	v_mad_i64_i32 v[32:33], s[12:13], v32, s89, v[2:3]
	global_load_ushort v214, v[32:33], off
	s_or_b64 exec, exec, s[78:79]
	s_mov_b64 exec, s[66:67]
	s_waitcnt vmcnt(0)
; __device__ __forceinline__ float bf2f(bf16_t v) { return __uint_as_float(((unsigned)v) << 16); }
; __device__ void lru_local_unit(const Params& p, unsigned char* smem, int unit) {
;     ...
; #pragma unroll 11
;   for (int e = tid; e < 131 * 64; e += HTHR) {
;     const int r = e >> 6, j = e & 63, tt = r - 3;
;     float v = 0.f;
;     if (c * 128 + tt >= 0) v = bf2f(proj[(size_t)(t0 + tt) * LDP + ch0 + j]);
;     R1[e] = v;
;   }
	s_and_saveexec_b64 s[76:77], s[4:5]
	v_cmp_lt_u32_e32 vcc, 0, v227
	v_lshlrev_b32_e32 v140, 16, v140
	s_and_saveexec_b64 s[80:81], vcc
	ds_write_b32 v226, v140
	s_or_b64 exec, exec, s[80:81]
	v_cmp_lt_u32_e32 vcc, 1, v227
	v_lshlrev_b32_e32 v141, 16, v141
	s_and_saveexec_b64 s[80:81], vcc
	ds_write_b32 v226, v141 offset:1024
	s_or_b64 exec, exec, s[80:81]
	v_cmp_lt_u32_e32 vcc, 2, v227
	v_lshlrev_b32_e32 v142, 16, v142
	s_and_saveexec_b64 s[80:81], vcc
	ds_write_b32 v226, v142 offset:2048
	s_or_b64 exec, exec, s[80:81]
	v_cmp_lt_u32_e32 vcc, 3, v227
	v_lshlrev_b32_e32 v143, 16, v143
	s_and_saveexec_b64 s[80:81], vcc
	ds_write_b32 v226, v143 offset:3072
	s_or_b64 exec, exec, s[80:81]
	v_cmp_lt_u32_e32 vcc, 4, v227
	v_lshlrev_b32_e32 v144, 16, v144
	s_and_saveexec_b64 s[80:81], vcc
	ds_write_b32 v226, v144 offset:4096
	s_or_b64 exec, exec, s[80:81]
	v_cmp_lt_u32_e32 vcc, 5, v227
	v_lshlrev_b32_e32 v145, 16, v145
	s_and_saveexec_b64 s[80:81], vcc
	ds_write_b32 v226, v145 offset:5120
	s_or_b64 exec, exec, s[80:81]
	v_cmp_lt_u32_e32 vcc, 6, v227
	v_lshlrev_b32_e32 v146, 16, v146
	s_and_saveexec_b64 s[80:81], vcc
	ds_write_b32 v226, v146 offset:6144
	s_or_b64 exec, exec, s[80:81]
	v_cmp_lt_u32_e32 vcc, 7, v227
	v_lshlrev_b32_e32 v147, 16, v147
	s_and_saveexec_b64 s[80:81], vcc
	ds_write_b32 v226, v147 offset:7168
	s_or_b64 exec, exec, s[80:81]
	v_cmp_lt_u32_e32 vcc, 8, v227
	v_lshlrev_b32_e32 v148, 16, v148
	s_and_saveexec_b64 s[80:81], vcc
	ds_write_b32 v226, v148 offset:8192
	s_or_b64 exec, exec, s[80:81]
	v_cmp_lt_u32_e32 vcc, 9, v227
	v_lshlrev_b32_e32 v149, 16, v149
	s_and_saveexec_b64 s[80:81], vcc
	ds_write_b32 v226, v149 offset:9216
	s_or_b64 exec, exec, s[80:81]
	s_or_b64 exec, exec, s[76:77]
	v_lshlrev_b32_e32 v215, 16, v215
	ds_write_b32 v26, v215
	v_lshlrev_b32_e32 v216, 16, v216
	ds_write_b32 v26, v216 offset:1024
	v_lshlrev_b32_e32 v217, 16, v217
	ds_write_b32 v26, v217 offset:2048
	v_lshlrev_b32_e32 v218, 16, v218
	ds_write_b32 v26, v218 offset:3072
	v_lshlrev_b32_e32 v219, 16, v219
	ds_write_b32 v26, v219 offset:4096
	v_lshlrev_b32_e32 v220, 16, v220
	ds_write_b32 v26, v220 offset:5120
	v_lshlrev_b32_e32 v221, 16, v221
	ds_write_b32 v26, v221 offset:6144
	v_lshlrev_b32_e32 v222, 16, v222
	ds_write_b32 v26, v222 offset:7168
	v_lshlrev_b32_e32 v223, 16, v223
	ds_write_b32 v26, v223 offset:8192
	v_lshlrev_b32_e32 v224, 16, v224
	ds_write_b32 v26, v224 offset:9216
	v_lshlrev_b32_e32 v225, 16, v225
	ds_write_b32 v26, v225 offset:10240
	s_mov_b64 exec, s[72:73]
	v_lshlrev_b32_e32 v193, 16, v193
	ds_write_b32 v26, v193 offset:11264
	v_lshlrev_b32_e32 v194, 16, v194
	ds_write_b32 v26, v194 offset:12288
	v_lshlrev_b32_e32 v195, 16, v195
	ds_write_b32 v26, v195 offset:13312
	v_lshlrev_b32_e32 v196, 16, v196
	ds_write_b32 v26, v196 offset:14336
	v_lshlrev_b32_e32 v197, 16, v197
	ds_write_b32 v26, v197 offset:15360
	v_lshlrev_b32_e32 v198, 16, v198
	ds_write_b32 v26, v198 offset:16384
	v_lshlrev_b32_e32 v199, 16, v199
	ds_write_b32 v26, v199 offset:17408
	v_lshlrev_b32_e32 v200, 16, v200
	ds_write_b32 v26, v200 offset:18432
	v_lshlrev_b32_e32 v201, 16, v201
	ds_write_b32 v26, v201 offset:19456
	v_lshlrev_b32_e32 v202, 16, v202
	ds_write_b32 v26, v202 offset:20480
	v_lshlrev_b32_e32 v203, 16, v203
	ds_write_b32 v26, v203 offset:21504
	s_mov_b64 exec, s[74:75]
	v_lshlrev_b32_e32 v204, 16, v204
	ds_write_b32 v26, v204 offset:22528
	v_lshlrev_b32_e32 v205, 16, v205
	ds_write_b32 v26, v205 offset:23552
	v_lshlrev_b32_e32 v206, 16, v206
	ds_write_b32 v26, v206 offset:24576
	v_lshlrev_b32_e32 v207, 16, v207
	ds_write_b32 v26, v207 offset:25600
	v_lshlrev_b32_e32 v208, 16, v208
	ds_write_b32 v26, v208 offset:26624
	v_lshlrev_b32_e32 v209, 16, v209
	ds_write_b32 v26, v209 offset:27648
	v_lshlrev_b32_e32 v210, 16, v210
	ds_write_b32 v26, v210 offset:28672
	v_lshlrev_b32_e32 v211, 16, v211
	ds_write_b32 v26, v211 offset:29696
	v_lshlrev_b32_e32 v212, 16, v212
	ds_write_b32 v26, v212 offset:30720
	v_lshlrev_b32_e32 v213, 16, v213
	ds_write_b32 v26, v213 offset:31744
	v_lshlrev_b32_e32 v214, 16, v214
	ds_write_b32 v26, v214 offset:32768
	s_mov_b64 exec, s[66:67]
	s_mov_b64 s[66:67], 0
